# v27 + gcoef token loop rewritten: all 20 loads per token issued up front (1 memory round trip per token instead of 3)
# speedup vs baseline: 1.0068x; 1.0001x over previous
.LBB0_596:
	s_mov_b32 s32, 0x10120000
	s_mov_b32 s33, 0
	s_mov_b32 s34, 0x10920000
	s_mov_b32 s35, 0
	s_mov_b32 s36, 0x11120000
	s_mov_b32 s37, 0
	s_mov_b32 s38, 0x11920000
	s_mov_b32 s39, 0
	s_mov_b32 s40, 0x12120000
	s_mov_b32 s41, 0
	s_mov_b32 s42, 0x12920000
	s_mov_b32 s43, 0
	s_mov_b32 s52, 0x13120000
	s_mov_b32 s53, 0
	s_mov_b32 s54, 0x13920000
	s_mov_b32 s55, 0
	s_mov_b32 s56, 0x1a520000
	s_mov_b32 s57, 0
	s_mov_b32 s60, 0x14120000
	s_mov_b32 s61, 0
	v_lshl_add_u64 v[6:7], v[4:5], 0, s[4:5]
	global_load_dwordx4 v[24:27], v[6:7], off offset:16
	global_load_dwordx4 v[28:31], v[6:7], off
	v_lshl_add_u64 v[6:7], v[2:3], 0, s[4:5]
	v_lshl_add_u64 v[8:9], v[6:7], 0, s[32:33]
	v_lshl_add_u64 v[10:11], v[6:7], 0, s[34:35]
	v_lshl_add_u64 v[12:13], v[6:7], 0, s[36:37]
	v_lshl_add_u64 v[14:15], v[6:7], 0, s[38:39]
	v_lshl_add_u64 v[16:17], v[6:7], 0, s[40:41]
	v_lshl_add_u64 v[18:19], v[6:7], 0, s[42:43]
	v_lshl_add_u64 v[60:61], v[6:7], 0, s[52:53]
	v_lshl_add_u64 v[62:63], v[6:7], 0, s[54:55]
	v_lshl_add_u64 v[38:39], v[6:7], 0, s[56:57]
	global_load_dword v41, v[8:9], off
	global_load_dword v42, v[10:11], off
	global_load_dword v43, v[12:13], off
	global_load_dword v44, v[14:15], off
	global_load_dword v45, v[16:17], off
	global_load_dword v46, v[18:19], off
	global_load_dword v47, v[60:61], off
	global_load_dword v48, v[62:63], off
	global_load_dword v49, v[8:9], off offset:256
	global_load_dword v50, v[10:11], off offset:256
	global_load_dword v51, v[12:13], off offset:256
	global_load_dword v52, v[14:15], off offset:256
	global_load_dword v53, v[16:17], off offset:256
	global_load_dword v54, v[18:19], off offset:256
	global_load_dword v55, v[60:61], off offset:256
	global_load_dword v56, v[62:63], off offset:256
	global_load_dword v57, v[38:39], off
	global_load_dword v58, v[38:39], off offset:256
	v_lshl_add_u64 v[6:7], v[6:7], 0, s[60:61]
	v_add_u32_e32 v0, s84, v0
	v_lshl_add_u64 v[2:3], v[2:3], 0, s[8:9]
	v_lshl_add_u64 v[4:5], v[4:5], 0, s[10:11]
	s_waitcnt vmcnt(10)
	v_add_f32_e32 v34, 0, v41
	v_add_f32_e32 v34, v34, v42
	v_add_f32_e32 v34, v34, v43
	v_add_f32_e32 v34, v34, v44
	v_add_f32_e32 v34, v34, v45
	v_add_f32_e32 v34, v34, v46
	v_add_f32_e32 v34, v34, v47
	v_add_f32_e32 v34, v34, v48
	v_mov_b32_e32 v32, v28
	v_mov_b32_e32 v33, v24
	v_mov_b32_e32 v24, v29
	v_mov_b32_e32 v28, v30
	v_mov_b32_e32 v29, v26
	v_mov_b32_e32 v26, v31
	v_pk_add_f32 v[24:25], v[32:33], v[24:25]
	v_pk_add_f32 v[26:27], v[28:29], v[26:27]
	v_pk_add_f32 v[24:25], v[24:25], v[26:27]
	v_add_f32_e32 v24, v24, v25
	v_fmamk_f32 v24, v24, 0x3a800000, v1
	v_mul_f32_e32 v25, 0x4b800000, v24
	v_cmp_gt_f32_e32 vcc, s12, v24
	s_nop 1
	v_cndmask_b32_e32 v24, v24, v25, vcc
	v_rsq_f32_e32 v24, v24
	s_nop 1
	v_mul_f32_e32 v23, 0x45800000, v24
	v_cndmask_b32_e32 v23, v24, v23, vcc
	v_mul_f32_e32 v23, 0x3c800000, v23
	v_mul_f32_e32 v24, v34, v23
	v_mul_f32_e32 v25, 0x3f3504f3, v24
	v_cmp_nlt_f32_e64 s[0:1], |v25|, 1.0
	s_and_saveexec_b64 s[30:31], s[0:1]
	s_xor_b64 s[0:1], exec, s[30:31]
	s_cbranch_execz .Lgc0_fa
	v_fma_f32 v26, |v25|, s19, v21
	v_fma_f32 v26, |v25|, v26, s20
	v_fma_f32 v26, |v25|, v26, s21
	v_fma_f32 v26, |v25|, v26, s22
	v_fma_f32 v26, |v25|, v26, s23
	v_fma_f32 v26, |v25|, v26, s24
	v_fma_f32 v26, |v25|, v26, |v25|
	v_mul_f32_e32 v27, 0xbfb8aa3b, v26
	v_fma_f32 v28, v26, s25, -v27
	v_rndne_f32_e32 v29, v27
	v_fmac_f32_e32 v28, 0xb2a5705f, v26
	v_sub_f32_e32 v27, v27, v29
	v_add_f32_e32 v27, v27, v28
	v_cvt_i32_f32_e32 v28, v29
	v_exp_f32_e32 v27, v27
	v_cmp_nlt_f32_e32 vcc, s26, v26
	v_ldexp_f32 v27, v27, v28
	s_nop 0
	v_cndmask_b32_e32 v27, 0, v27, vcc
	v_cmp_ngt_f32_e32 vcc, s27, v26
	s_nop 1
	v_cndmask_b32_e32 v26, v22, v27, vcc
	v_sub_f32_e32 v26, 1.0, v26
.Lgc0_fa:
	s_andn2_saveexec_b64 s[0:1], s[0:1]
	s_cbranch_execz .Lgc0_fb
	v_mul_f32_e32 v26, v25, v25
	v_fmamk_f32 v27, v26, 0xba1345e1, v20
	v_fmaak_f32 v27, v26, v27, 0xbcdac9b8
	v_fmaak_f32 v27, v26, v27, 0x3de703be
	v_fmaak_f32 v27, v26, v27, 0xbec09330
	v_fmaak_f32 v26, v26, v27, 0x3e0375d0
	v_fma_f32 v26, |v25|, v26, |v25|
.Lgc0_fb:
	s_or_b64 exec, exec, s[0:1]
	v_bfi_b32 v35, s28, v26, v25
	v_mul_f32_e32 v40, 0.5, v24
	v_add_f32_e32 v35, 1.0, v35
	v_mul_f32_e32 v40, v40, v35
	s_waitcnt vmcnt(0)
	v_mul_f32_e32 v40, v57, v40
	v_mul_f32_e32 v40, 0x3d800000, v40
	global_store_dword v[6:7], v40, off
	v_add_f32_e32 v34, 0, v49
	v_add_f32_e32 v34, v34, v50
	v_add_f32_e32 v34, v34, v51
	v_add_f32_e32 v34, v34, v52
	v_add_f32_e32 v34, v34, v53
	v_add_f32_e32 v34, v34, v54
	v_add_f32_e32 v34, v34, v55
	v_add_f32_e32 v34, v34, v56
	v_mul_f32_e32 v24, v23, v34
	v_mul_f32_e32 v25, 0x3f3504f3, v24
	v_cmp_nlt_f32_e64 s[0:1], |v25|, 1.0
	s_and_saveexec_b64 s[30:31], s[0:1]
	s_xor_b64 s[0:1], exec, s[30:31]
	s_cbranch_execz .Lgc0_sa
	v_fma_f32 v26, |v25|, s19, v21
	v_fma_f32 v26, |v25|, v26, s20
	v_fma_f32 v26, |v25|, v26, s21
	v_fma_f32 v26, |v25|, v26, s22
	v_fma_f32 v26, |v25|, v26, s23
	v_fma_f32 v26, |v25|, v26, s24
	v_fma_f32 v26, |v25|, v26, |v25|
	v_mul_f32_e32 v27, 0xbfb8aa3b, v26
	v_fma_f32 v28, v26, s25, -v27
	v_rndne_f32_e32 v29, v27
	v_fmac_f32_e32 v28, 0xb2a5705f, v26
	v_sub_f32_e32 v27, v27, v29
	v_add_f32_e32 v27, v27, v28
	v_cvt_i32_f32_e32 v28, v29
	v_exp_f32_e32 v27, v27
	v_cmp_nlt_f32_e32 vcc, s26, v26
	v_ldexp_f32 v27, v27, v28
	s_nop 0
	v_cndmask_b32_e32 v27, 0, v27, vcc
	v_cmp_ngt_f32_e32 vcc, s27, v26
	s_nop 1
	v_cndmask_b32_e32 v26, v22, v27, vcc
	v_sub_f32_e32 v26, 1.0, v26

.Lgc0_sb:
	s_or_b64 exec, exec, s[0:1]
	v_bfi_b32 v35, s28, v26, v25
	v_mul_f32_e32 v40, 0.5, v24
	v_add_f32_e32 v35, 1.0, v35
	v_mul_f32_e32 v40, v40, v35
	v_mul_f32_e32 v40, v58, v40
	v_mul_f32_e32 v40, 0x3d800000, v40
	global_store_dword v[6:7], v40, off offset:256
	v_cmp_lt_i32_e64 s[0:1], s29, v0
	s_or_b64 s[2:3], s[0:1], s[2:3]
	s_andn2_b64 exec, exec, s[2:3]
	s_cbranch_execnz .LBB0_596
